# phase 4 dealing: blocks <256, odd block of group k takes the short MLA item handed off by group 3-k (largest hand-off to lightest receiver)
# baseline (speedup 1.0000x reference)
; DI void phase_attn2(const Params& p, char* smem) {
;   for (int it = blockIdx.x; it < 1024; it += gridDim.x) {
;     const int j = (it & 511) >> 1;
;     const int idx = (it < 512) ? j : (511 - j);
;     if (it & 1) attn_item<1>(p, idx, smem); else attn_item<3>(p, idx, smem);
;   }
; }
.Lp4_tail:
	s_cmpk_lt_u32 s2, 0x100
	s_cbranch_scc0 .LBB0_145
	s_bitcmp1_b32 s93, 0
	s_cbranch_scc0 .LBB0_145
	s_cmpk_ge_i32 s93, 0x600
	s_cbranch_scc1 .LBB0_145
	s_lshr_b32 s3, s2, 6
	s_lshl_b32 s3, s3, 7
	s_sub_i32 s93, s93, 0x201
	s_addk_i32 s93, 0xc0
	s_sub_i32 s93, s93, s3
